# residual-add (FFN_DOWN/WO) epilogue rewritten by hand: in-place packed math, permlane16/32 swaps for the row sums instead of LDS bpermute, loads prefetched, waits count only younger loads
# baseline (speedup 1.0000x reference)
; #define LAS __attribute__((address_space(3)))
; DI u32x2 pk4(f32x4 v) { u32x2 r; r.x = cvt_pk(v[0], v[1]); r.y = cvt_pk(v[2], v[3]); return r; }
; DI void gemm_phase(LAS unsigned char* lds, const GemmDesc& d, float* __restrict__ X) {
;     ...
;     } else if (EPI_ON(EPI_RESID)) {
;       LAS float* red = (LAS float*)(lds + 133120); const float alpha = d.K == FF ? 0.5f : 1.f;
; #pragma unroll
;       for (int ai = 0; ai < 2; ++ai)
; #pragma unroll
;         for (int m = 0; m < 4; ++m) {
;           const int row = pm * 256 + 128 * ai + 16 * m + rb; float ss = 0.f;
; #pragma unroll
;           for (int bj = 0; bj < 2; ++bj) {
;             const size_t o = (size_t)row * DM + pn * 256 + 128 * bj + cb;
;             const u32x4 xw = *(const u32x4*)(d.O0 + o); u32x4 ow;
; #pragma unroll
;             for (int n = 0; n < 2; ++n) {
;               const unsigned w0 = n ? xw.z : xw.x, w1 = n ? xw.w : xw.y;
;               f32x4 xo; xo[0] = __uint_as_float(w0 << 16); xo[1] = __uint_as_float(w0 & 0xffff0000u); xo[2] = __uint_as_float(w1 << 16); xo[3] = __uint_as_float(w1 & 0xffff0000u);
;               const f32x4 xn = xo + acc[ai][bj][m][n] * alpha;
;               ss += (xn[0] * xn[0] + xn[1] * xn[1]) + (xn[2] * xn[2] + xn[3] * xn[3]);
;               const u32x2 pw = pk4(xn); if (n) { ow.z = pw.x; ow.w = pw.y; } else { ow.x = pw.x; ow.y = pw.y; }
;             }
;             *(u32x4*)(d.O0 + o) = ow;
;           }
;           ss += __shfl_xor(ss, 16); ss += __shfl_xor(ss, 32);
;           if (fq == 0) red[wc * 256 + 128 * ai + 16 * m + rb] = ss;
;           asm volatile("" ::: "memory");
;         }
.LBB0_522:
	s_andn2_b64 vcc, exec, s[44:45]
	s_cbranch_vccnz .LBB0_542
	s_lshl_b32 s46, s97, 8
	s_lshl_b32 s6, s68, 8
	v_add_u32_e32 v132, s46, v163
	s_waitcnt lgkmcnt(0)
	v_or_b32_e32 v130, s6, v182
	v_lshlrev_b32_e32 v243, 11, v132
	v_lshl_add_u32 v243, v130, 1, v243
	global_load_dwordx4 v[142:145], v243, s[28:29]
	global_load_dwordx4 v[166:169], v243, s[28:29] offset:256
	v_add_u32_e32 v252, 0x8000, v243
	global_load_dwordx4 v[170:173], v252, s[28:29]
	v_add_u32_e32 v252, 0x8000, v243
	global_load_dwordx4 v[184:187], v252, s[28:29] offset:256
	v_add_u32_e32 v252, 0x10000, v243
	global_load_dwordx4 v[188:191], v252, s[28:29]
	v_add_u32_e32 v252, 0x10000, v243
	global_load_dwordx4 v[216:219], v252, s[28:29] offset:256
	v_add_u32_e32 v252, 0x18000, v243
	global_load_dwordx4 v[222:225], v252, s[28:29]
	v_add_u32_e32 v252, 0x18000, v243
	global_load_dwordx4 v[226:229], v252, s[28:29] offset:256
	v_add_u32_e32 v252, 0x40000, v243
	global_load_dwordx4 v[230:233], v252, s[28:29]
	v_add_u32_e32 v252, 0x40000, v243
	global_load_dwordx4 v[234:237], v252, s[28:29] offset:256
	v_add_u32_e32 v252, 0x48000, v243
	global_load_dwordx4 v[244:247], v252, s[28:29]
	v_add_u32_e32 v252, 0x48000, v243
	global_load_dwordx4 v[248:251], v252, s[28:29] offset:256
	s_lshl_b32 s6, s20, 10
	s_add_i32 s6, s6, 0x20800
	v_cmp_eq_u32_e32 vcc, 0, v179
	v_lshl_add_u32 v0, v163, 2, s6
	s_waitcnt vmcnt(11)
	v_lshlrev_b32_e32 v130, 16, v142
	v_and_b32_e32 v131, 0xffff0000, v142
	v_lshlrev_b32_e32 v132, 16, v143
	v_and_b32_e32 v133, 0xffff0000, v143
	v_lshlrev_b32_e32 v134, 16, v144
	v_and_b32_e32 v135, 0xffff0000, v144
	v_lshlrev_b32_e32 v136, 16, v145
	v_and_b32_e32 v137, 0xffff0000, v145
	v_add_u32_e32 v252, 0x50000, v243
	global_load_dwordx4 v[142:145], v252, s[28:29]
	v_pk_fma_f32 v[126:127], s[60:61], v[126:127], v[130:131]
	v_pk_fma_f32 v[128:129], s[66:67], v[128:129], v[132:133]
	v_pk_fma_f32 v[122:123], s[60:61], v[122:123], v[134:135]
	v_pk_fma_f32 v[124:125], s[66:67], v[124:125], v[136:137]
	v_pk_mul_f32 v[138:139], v[126:127], v[126:127]
	v_pk_mul_f32 v[140:141], v[128:129], v[128:129]
	v_pk_fma_f32 v[138:139], v[122:123], v[122:123], v[138:139]
	v_pk_fma_f32 v[140:141], v[124:125], v[124:125], v[140:141]
	v_cvt_pk_bf16_f32 v126, v126, v127
	v_cvt_pk_bf16_f32 v127, v128, v129
	v_cvt_pk_bf16_f32 v128, v122, v123
	v_cvt_pk_bf16_f32 v129, v124, v125
	global_store_dwordx4 v243, v[126:129], s[28:29]
	s_waitcnt vmcnt(11)
	v_lshlrev_b32_e32 v130, 16, v166
	v_and_b32_e32 v131, 0xffff0000, v166
	v_lshlrev_b32_e32 v132, 16, v167
	v_and_b32_e32 v133, 0xffff0000, v167
	v_lshlrev_b32_e32 v134, 16, v168
	v_and_b32_e32 v135, 0xffff0000, v168
	v_lshlrev_b32_e32 v136, 16, v169
	v_and_b32_e32 v137, 0xffff0000, v169
	v_add_u32_e32 v252, 0x50000, v243
	global_load_dwordx4 v[166:169], v252, s[28:29] offset:256
	v_pk_fma_f32 v[118:119], s[60:61], v[118:119], v[130:131]
	v_pk_fma_f32 v[120:121], s[66:67], v[120:121], v[132:133]
	v_pk_fma_f32 v[114:115], s[60:61], v[114:115], v[134:135]
	v_pk_fma_f32 v[116:117], s[66:67], v[116:117], v[136:137]
	v_pk_fma_f32 v[138:139], v[118:119], v[118:119], v[138:139]
	v_pk_fma_f32 v[140:141], v[120:121], v[120:121], v[140:141]
	v_pk_fma_f32 v[138:139], v[114:115], v[114:115], v[138:139]
	v_pk_fma_f32 v[140:141], v[116:117], v[116:117], v[140:141]
	v_cvt_pk_bf16_f32 v118, v118, v119
	v_cvt_pk_bf16_f32 v119, v120, v121
	v_cvt_pk_bf16_f32 v120, v114, v115
	v_cvt_pk_bf16_f32 v121, v116, v117
	global_store_dwordx4 v243, v[118:121], s[28:29] offset:256
	v_pk_add_f32 v[138:139], v[138:139], v[140:141]
	s_nop 0
	v_add_f32_e32 v114, v138, v139
	v_add_u32_e32 v253, 0x8000, v243
	s_waitcnt vmcnt(11)
	v_lshlrev_b32_e32 v130, 16, v170
	v_and_b32_e32 v131, 0xffff0000, v170
	v_lshlrev_b32_e32 v132, 16, v171
	v_and_b32_e32 v133, 0xffff0000, v171
	v_lshlrev_b32_e32 v134, 16, v172
	v_and_b32_e32 v135, 0xffff0000, v172
	v_lshlrev_b32_e32 v136, 16, v173
	v_and_b32_e32 v137, 0xffff0000, v173
	v_add_u32_e32 v252, 0x58000, v243
	global_load_dwordx4 v[170:173], v252, s[28:29]
	v_pk_fma_f32 v[110:111], s[60:61], v[110:111], v[130:131]
	v_pk_fma_f32 v[112:113], s[66:67], v[112:113], v[132:133]
	v_pk_fma_f32 v[106:107], s[60:61], v[106:107], v[134:135]
	v_pk_fma_f32 v[108:109], s[66:67], v[108:109], v[136:137]
	v_pk_mul_f32 v[138:139], v[110:111], v[110:111]
	v_pk_mul_f32 v[140:141], v[112:113], v[112:113]
	v_pk_fma_f32 v[138:139], v[106:107], v[106:107], v[138:139]
	v_pk_fma_f32 v[140:141], v[108:109], v[108:109], v[140:141]
	v_cvt_pk_bf16_f32 v110, v110, v111
	v_cvt_pk_bf16_f32 v111, v112, v113
	v_cvt_pk_bf16_f32 v112, v106, v107
	v_cvt_pk_bf16_f32 v113, v108, v109
	global_store_dwordx4 v253, v[110:113], s[28:29]
	s_waitcnt vmcnt(11)
	v_lshlrev_b32_e32 v130, 16, v184
	v_and_b32_e32 v131, 0xffff0000, v184
	v_lshlrev_b32_e32 v132, 16, v185
	v_and_b32_e32 v133, 0xffff0000, v185
	v_lshlrev_b32_e32 v134, 16, v186
	v_and_b32_e32 v135, 0xffff0000, v186
	v_lshlrev_b32_e32 v136, 16, v187
	v_and_b32_e32 v137, 0xffff0000, v187
	v_add_u32_e32 v252, 0x58000, v243
	global_load_dwordx4 v[184:187], v252, s[28:29] offset:256
	v_pk_fma_f32 v[102:103], s[60:61], v[102:103], v[130:131]
	v_pk_fma_f32 v[104:105], s[66:67], v[104:105], v[132:133]
	v_pk_fma_f32 v[98:99], s[60:61], v[98:99], v[134:135]
	v_pk_fma_f32 v[100:101], s[66:67], v[100:101], v[136:137]
	v_pk_fma_f32 v[138:139], v[102:103], v[102:103], v[138:139]
	v_pk_fma_f32 v[140:141], v[104:105], v[104:105], v[140:141]
	v_pk_fma_f32 v[138:139], v[98:99], v[98:99], v[138:139]
	v_pk_fma_f32 v[140:141], v[100:101], v[100:101], v[140:141]
	v_cvt_pk_bf16_f32 v102, v102, v103
	v_cvt_pk_bf16_f32 v103, v104, v105
	v_cvt_pk_bf16_f32 v104, v98, v99
	v_cvt_pk_bf16_f32 v105, v100, v101
	global_store_dwordx4 v253, v[102:105], s[28:29] offset:256
	v_pk_add_f32 v[138:139], v[138:139], v[140:141]
	s_nop 0
	v_add_f32_e32 v115, v138, v139
	v_add_u32_e32 v253, 0x10000, v243
	s_waitcnt vmcnt(11)
; #define LAS __attribute__((address_space(3)))
; DI u32x2 pk4(f32x4 v) { u32x2 r; r.x = cvt_pk(v[0], v[1]); r.y = cvt_pk(v[2], v[3]); return r; }
; DI void gemm_phase(LAS unsigned char* lds, const GemmDesc& d, float* __restrict__ X) {
;     ...
;     } else if (EPI_ON(EPI_RESID)) {
;       LAS float* red = (LAS float*)(lds + 133120); const float alpha = d.K == FF ? 0.5f : 1.f;
; #pragma unroll
;       for (int ai = 0; ai < 2; ++ai)
; #pragma unroll
;         for (int m = 0; m < 4; ++m) {
;           const int row = pm * 256 + 128 * ai + 16 * m + rb; float ss = 0.f;
; #pragma unroll
;           for (int bj = 0; bj < 2; ++bj) {
;             const size_t o = (size_t)row * DM + pn * 256 + 128 * bj + cb;
;             const u32x4 xw = *(const u32x4*)(d.O0 + o); u32x4 ow;
; #pragma unroll
;             for (int n = 0; n < 2; ++n) {
;               const unsigned w0 = n ? xw.z : xw.x, w1 = n ? xw.w : xw.y;
;               f32x4 xo; xo[0] = __uint_as_float(w0 << 16); xo[1] = __uint_as_float(w0 & 0xffff0000u); xo[2] = __uint_as_float(w1 << 16); xo[3] = __uint_as_float(w1 & 0xffff0000u);
;               const f32x4 xn = xo + acc[ai][bj][m][n] * alpha;
;               ss += (xn[0] * xn[0] + xn[1] * xn[1]) + (xn[2] * xn[2] + xn[3] * xn[3]);
;               const u32x2 pw = pk4(xn); if (n) { ow.z = pw.x; ow.w = pw.y; } else { ow.x = pw.x; ow.y = pw.y; }
;             }
;             *(u32x4*)(d.O0 + o) = ow;
;           }
;           ss += __shfl_xor(ss, 16); ss += __shfl_xor(ss, 32);
;           if (fq == 0) red[wc * 256 + 128 * ai + 16 * m + rb] = ss;
;           asm volatile("" ::: "memory");
;         }
	v_lshlrev_b32_e32 v130, 16, v188
	v_and_b32_e32 v131, 0xffff0000, v188
	v_lshlrev_b32_e32 v132, 16, v189
	v_and_b32_e32 v133, 0xffff0000, v189
	v_lshlrev_b32_e32 v134, 16, v190
	v_and_b32_e32 v135, 0xffff0000, v190
	v_lshlrev_b32_e32 v136, 16, v191
	v_and_b32_e32 v137, 0xffff0000, v191
	v_pk_fma_f32 v[94:95], s[60:61], v[94:95], v[130:131]
	v_pk_fma_f32 v[96:97], s[66:67], v[96:97], v[132:133]
	v_pk_fma_f32 v[90:91], s[60:61], v[90:91], v[134:135]
	v_pk_fma_f32 v[92:93], s[66:67], v[92:93], v[136:137]
	v_pk_mul_f32 v[138:139], v[94:95], v[94:95]
	v_pk_mul_f32 v[140:141], v[96:97], v[96:97]
	v_pk_fma_f32 v[138:139], v[90:91], v[90:91], v[138:139]
	v_pk_fma_f32 v[140:141], v[92:93], v[92:93], v[140:141]
	v_cvt_pk_bf16_f32 v94, v94, v95
	v_cvt_pk_bf16_f32 v95, v96, v97
	v_cvt_pk_bf16_f32 v96, v90, v91
	v_cvt_pk_bf16_f32 v97, v92, v93
	global_store_dwordx4 v253, v[94:97], s[28:29]
	s_waitcnt vmcnt(10)
	v_lshlrev_b32_e32 v130, 16, v216
	v_and_b32_e32 v131, 0xffff0000, v216
	v_lshlrev_b32_e32 v132, 16, v217
	v_and_b32_e32 v133, 0xffff0000, v217
	v_lshlrev_b32_e32 v134, 16, v218
	v_and_b32_e32 v135, 0xffff0000, v218
	v_lshlrev_b32_e32 v136, 16, v219
	v_and_b32_e32 v137, 0xffff0000, v219
	v_pk_fma_f32 v[86:87], s[60:61], v[86:87], v[130:131]
	v_pk_fma_f32 v[88:89], s[66:67], v[88:89], v[132:133]
	v_pk_fma_f32 v[82:83], s[60:61], v[82:83], v[134:135]
	v_pk_fma_f32 v[84:85], s[66:67], v[84:85], v[136:137]
	v_pk_fma_f32 v[138:139], v[86:87], v[86:87], v[138:139]
	v_pk_fma_f32 v[140:141], v[88:89], v[88:89], v[140:141]
	v_pk_fma_f32 v[138:139], v[82:83], v[82:83], v[138:139]
	v_pk_fma_f32 v[140:141], v[84:85], v[84:85], v[140:141]
	v_cvt_pk_bf16_f32 v86, v86, v87
	v_cvt_pk_bf16_f32 v87, v88, v89
	v_cvt_pk_bf16_f32 v88, v82, v83
	v_cvt_pk_bf16_f32 v89, v84, v85
	global_store_dwordx4 v253, v[86:89], s[28:29] offset:256
	v_pk_add_f32 v[138:139], v[138:139], v[140:141]
	s_nop 0
	v_add_f32_e32 v116, v138, v139
	v_add_u32_e32 v253, 0x18000, v243
	s_waitcnt vmcnt(9)
	v_lshlrev_b32_e32 v130, 16, v222
	v_and_b32_e32 v131, 0xffff0000, v222
	v_lshlrev_b32_e32 v132, 16, v223
	v_and_b32_e32 v133, 0xffff0000, v223
	v_lshlrev_b32_e32 v134, 16, v224
	v_and_b32_e32 v135, 0xffff0000, v224
	v_lshlrev_b32_e32 v136, 16, v225
	v_and_b32_e32 v137, 0xffff0000, v225
	v_pk_fma_f32 v[78:79], s[60:61], v[78:79], v[130:131]
	v_pk_fma_f32 v[80:81], s[66:67], v[80:81], v[132:133]
	v_pk_fma_f32 v[74:75], s[60:61], v[74:75], v[134:135]
	v_pk_fma_f32 v[76:77], s[66:67], v[76:77], v[136:137]
	v_pk_mul_f32 v[138:139], v[78:79], v[78:79]
	v_pk_mul_f32 v[140:141], v[80:81], v[80:81]
	v_pk_fma_f32 v[138:139], v[74:75], v[74:75], v[138:139]
	v_pk_fma_f32 v[140:141], v[76:77], v[76:77], v[140:141]
	v_cvt_pk_bf16_f32 v78, v78, v79
	v_cvt_pk_bf16_f32 v79, v80, v81
	v_cvt_pk_bf16_f32 v80, v74, v75
	v_cvt_pk_bf16_f32 v81, v76, v77
	global_store_dwordx4 v253, v[78:81], s[28:29]
	s_waitcnt vmcnt(8)
	v_lshlrev_b32_e32 v130, 16, v226
	v_and_b32_e32 v131, 0xffff0000, v226
	v_lshlrev_b32_e32 v132, 16, v227
	v_and_b32_e32 v133, 0xffff0000, v227
	v_lshlrev_b32_e32 v134, 16, v228
	v_and_b32_e32 v135, 0xffff0000, v228
	v_lshlrev_b32_e32 v136, 16, v229
	v_and_b32_e32 v137, 0xffff0000, v229
	v_pk_fma_f32 v[70:71], s[60:61], v[70:71], v[130:131]
	v_pk_fma_f32 v[72:73], s[66:67], v[72:73], v[132:133]
	v_pk_fma_f32 v[66:67], s[60:61], v[66:67], v[134:135]
	v_pk_fma_f32 v[68:69], s[66:67], v[68:69], v[136:137]
	v_pk_fma_f32 v[138:139], v[70:71], v[70:71], v[138:139]
	v_pk_fma_f32 v[140:141], v[72:73], v[72:73], v[140:141]
	v_pk_fma_f32 v[138:139], v[66:67], v[66:67], v[138:139]
	v_pk_fma_f32 v[140:141], v[68:69], v[68:69], v[140:141]
	v_cvt_pk_bf16_f32 v70, v70, v71
	v_cvt_pk_bf16_f32 v71, v72, v73
	v_cvt_pk_bf16_f32 v72, v66, v67
	v_cvt_pk_bf16_f32 v73, v68, v69
	global_store_dwordx4 v253, v[70:73], s[28:29] offset:256
	v_pk_add_f32 v[138:139], v[138:139], v[140:141]
	s_nop 0
	v_add_f32_e32 v117, v138, v139
	v_add_u32_e32 v253, 0x40000, v243
	s_waitcnt vmcnt(7)
	v_lshlrev_b32_e32 v130, 16, v230
	v_and_b32_e32 v131, 0xffff0000, v230
	v_lshlrev_b32_e32 v132, 16, v231
	v_and_b32_e32 v133, 0xffff0000, v231
	v_lshlrev_b32_e32 v134, 16, v232
	v_and_b32_e32 v135, 0xffff0000, v232
	v_lshlrev_b32_e32 v136, 16, v233
	v_and_b32_e32 v137, 0xffff0000, v233
	v_pk_fma_f32 v[62:63], s[60:61], v[62:63], v[130:131]
	v_pk_fma_f32 v[64:65], s[66:67], v[64:65], v[132:133]
	v_pk_fma_f32 v[58:59], s[60:61], v[58:59], v[134:135]
	v_pk_fma_f32 v[60:61], s[66:67], v[60:61], v[136:137]
	v_pk_mul_f32 v[138:139], v[62:63], v[62:63]
	v_pk_mul_f32 v[140:141], v[64:65], v[64:65]
	v_pk_fma_f32 v[138:139], v[58:59], v[58:59], v[138:139]
	v_pk_fma_f32 v[140:141], v[60:61], v[60:61], v[140:141]
	v_cvt_pk_bf16_f32 v62, v62, v63
	v_cvt_pk_bf16_f32 v63, v64, v65
	v_cvt_pk_bf16_f32 v64, v58, v59
	v_cvt_pk_bf16_f32 v65, v60, v61
	global_store_dwordx4 v253, v[62:65], s[28:29]
	s_waitcnt vmcnt(6)
	v_lshlrev_b32_e32 v130, 16, v234
	v_and_b32_e32 v131, 0xffff0000, v234
	v_lshlrev_b32_e32 v132, 16, v235
	v_and_b32_e32 v133, 0xffff0000, v235
	v_lshlrev_b32_e32 v134, 16, v236
	v_and_b32_e32 v135, 0xffff0000, v236
	v_lshlrev_b32_e32 v136, 16, v237
	v_and_b32_e32 v137, 0xffff0000, v237
	v_pk_fma_f32 v[54:55], s[60:61], v[54:55], v[130:131]
	v_pk_fma_f32 v[56:57], s[66:67], v[56:57], v[132:133]
	v_pk_fma_f32 v[50:51], s[60:61], v[50:51], v[134:135]
	v_pk_fma_f32 v[52:53], s[66:67], v[52:53], v[136:137]
	v_pk_fma_f32 v[138:139], v[54:55], v[54:55], v[138:139]
	v_pk_fma_f32 v[140:141], v[56:57], v[56:57], v[140:141]
	v_pk_fma_f32 v[138:139], v[50:51], v[50:51], v[138:139]
	v_pk_fma_f32 v[140:141], v[52:53], v[52:53], v[140:141]
	v_cvt_pk_bf16_f32 v54, v54, v55
	v_cvt_pk_bf16_f32 v55, v56, v57
	v_cvt_pk_bf16_f32 v56, v50, v51
	v_cvt_pk_bf16_f32 v57, v52, v53
	global_store_dwordx4 v253, v[54:57], s[28:29] offset:256
	v_pk_add_f32 v[138:139], v[138:139], v[140:141]
	s_nop 0
	v_add_f32_e32 v122, v138, v139
	v_add_u32_e32 v253, 0x48000, v243
	s_waitcnt vmcnt(5)
; DI u32x2 pk4(f32x4 v) { u32x2 r; r.x = cvt_pk(v[0], v[1]); r.y = cvt_pk(v[2], v[3]); return r; }
; DI void gemm_phase(LAS unsigned char* lds, const GemmDesc& d, float* __restrict__ X) {
;     ...
;         for (int m = 0; m < 4; ++m) {
;           const int row = pm * 256 + 128 * ai + 16 * m + rb; float ss = 0.f;
; #pragma unroll
;           for (int bj = 0; bj < 2; ++bj) {
;             const size_t o = (size_t)row * DM + pn * 256 + 128 * bj + cb;
;             const u32x4 xw = *(const u32x4*)(d.O0 + o); u32x4 ow;
; #pragma unroll
;             for (int n = 0; n < 2; ++n) {
;               const unsigned w0 = n ? xw.z : xw.x, w1 = n ? xw.w : xw.y;
;               f32x4 xo; xo[0] = __uint_as_float(w0 << 16); xo[1] = __uint_as_float(w0 & 0xffff0000u); xo[2] = __uint_as_float(w1 << 16); xo[3] = __uint_as_float(w1 & 0xffff0000u);
;               const f32x4 xn = xo + acc[ai][bj][m][n] * alpha;
;               ss += (xn[0] * xn[0] + xn[1] * xn[1]) + (xn[2] * xn[2] + xn[3] * xn[3]);
;               const u32x2 pw = pk4(xn); if (n) { ow.z = pw.x; ow.w = pw.y; } else { ow.x = pw.x; ow.y = pw.y; }
;             }
;             *(u32x4*)(d.O0 + o) = ow;
;           }
;           ss += __shfl_xor(ss, 16); ss += __shfl_xor(ss, 32);
;           if (fq == 0) red[wc * 256 + 128 * ai + 16 * m + rb] = ss;
	v_lshlrev_b32_e32 v130, 16, v244
	v_and_b32_e32 v131, 0xffff0000, v244
	v_lshlrev_b32_e32 v132, 16, v245
	v_and_b32_e32 v133, 0xffff0000, v245
	v_lshlrev_b32_e32 v134, 16, v246
	v_and_b32_e32 v135, 0xffff0000, v246
	v_lshlrev_b32_e32 v136, 16, v247
	v_and_b32_e32 v137, 0xffff0000, v247
	v_pk_fma_f32 v[46:47], s[60:61], v[46:47], v[130:131]
	v_pk_fma_f32 v[48:49], s[66:67], v[48:49], v[132:133]
	v_pk_fma_f32 v[42:43], s[60:61], v[42:43], v[134:135]
	v_pk_fma_f32 v[44:45], s[66:67], v[44:45], v[136:137]
	v_pk_mul_f32 v[138:139], v[46:47], v[46:47]
	v_pk_mul_f32 v[140:141], v[48:49], v[48:49]
	v_pk_fma_f32 v[138:139], v[42:43], v[42:43], v[138:139]
	v_pk_fma_f32 v[140:141], v[44:45], v[44:45], v[140:141]
	v_cvt_pk_bf16_f32 v46, v46, v47
	v_cvt_pk_bf16_f32 v47, v48, v49
	v_cvt_pk_bf16_f32 v48, v42, v43
	v_cvt_pk_bf16_f32 v49, v44, v45
	global_store_dwordx4 v253, v[46:49], s[28:29]
	s_waitcnt vmcnt(4)
	v_lshlrev_b32_e32 v130, 16, v248
	v_and_b32_e32 v131, 0xffff0000, v248
	v_lshlrev_b32_e32 v132, 16, v249
	v_and_b32_e32 v133, 0xffff0000, v249
	v_lshlrev_b32_e32 v134, 16, v250
	v_and_b32_e32 v135, 0xffff0000, v250
	v_lshlrev_b32_e32 v136, 16, v251
	v_and_b32_e32 v137, 0xffff0000, v251
	v_pk_fma_f32 v[38:39], s[60:61], v[38:39], v[130:131]
	v_pk_fma_f32 v[40:41], s[66:67], v[40:41], v[132:133]
	v_pk_fma_f32 v[34:35], s[60:61], v[34:35], v[134:135]
	v_pk_fma_f32 v[36:37], s[66:67], v[36:37], v[136:137]
	v_pk_fma_f32 v[138:139], v[38:39], v[38:39], v[138:139]
	v_pk_fma_f32 v[140:141], v[40:41], v[40:41], v[140:141]
	v_pk_fma_f32 v[138:139], v[34:35], v[34:35], v[138:139]
	v_pk_fma_f32 v[140:141], v[36:37], v[36:37], v[140:141]
	v_cvt_pk_bf16_f32 v38, v38, v39
	v_cvt_pk_bf16_f32 v39, v40, v41
	v_cvt_pk_bf16_f32 v40, v34, v35
	v_cvt_pk_bf16_f32 v41, v36, v37
	global_store_dwordx4 v253, v[38:41], s[28:29] offset:256
	v_pk_add_f32 v[138:139], v[138:139], v[140:141]
	s_nop 0
	v_add_f32_e32 v123, v138, v139
	v_add_u32_e32 v253, 0x50000, v243
	s_waitcnt vmcnt(3)
	v_lshlrev_b32_e32 v130, 16, v142
	v_and_b32_e32 v131, 0xffff0000, v142
	v_lshlrev_b32_e32 v132, 16, v143
	v_and_b32_e32 v133, 0xffff0000, v143
	v_lshlrev_b32_e32 v134, 16, v144
	v_and_b32_e32 v135, 0xffff0000, v144
	v_lshlrev_b32_e32 v136, 16, v145
	v_and_b32_e32 v137, 0xffff0000, v145
	v_pk_fma_f32 v[30:31], s[60:61], v[30:31], v[130:131]
	v_pk_fma_f32 v[32:33], s[66:67], v[32:33], v[132:133]
	v_pk_fma_f32 v[26:27], s[60:61], v[26:27], v[134:135]
	v_pk_fma_f32 v[28:29], s[66:67], v[28:29], v[136:137]
	v_pk_mul_f32 v[138:139], v[30:31], v[30:31]
	v_pk_mul_f32 v[140:141], v[32:33], v[32:33]
	v_pk_fma_f32 v[138:139], v[26:27], v[26:27], v[138:139]
	v_pk_fma_f32 v[140:141], v[28:29], v[28:29], v[140:141]
	v_cvt_pk_bf16_f32 v30, v30, v31
	v_cvt_pk_bf16_f32 v31, v32, v33
	v_cvt_pk_bf16_f32 v32, v26, v27
	v_cvt_pk_bf16_f32 v33, v28, v29
	global_store_dwordx4 v253, v[30:33], s[28:29]
	s_waitcnt vmcnt(2)
	v_lshlrev_b32_e32 v130, 16, v166
	v_and_b32_e32 v131, 0xffff0000, v166
	v_lshlrev_b32_e32 v132, 16, v167
	v_and_b32_e32 v133, 0xffff0000, v167
	v_lshlrev_b32_e32 v134, 16, v168
	v_and_b32_e32 v135, 0xffff0000, v168
	v_lshlrev_b32_e32 v136, 16, v169
	v_and_b32_e32 v137, 0xffff0000, v169
	v_pk_fma_f32 v[22:23], s[60:61], v[22:23], v[130:131]
	v_pk_fma_f32 v[24:25], s[66:67], v[24:25], v[132:133]
	v_pk_fma_f32 v[18:19], s[60:61], v[18:19], v[134:135]
	v_pk_fma_f32 v[20:21], s[66:67], v[20:21], v[136:137]
	v_pk_fma_f32 v[138:139], v[22:23], v[22:23], v[138:139]
	v_pk_fma_f32 v[140:141], v[24:25], v[24:25], v[140:141]
	v_pk_fma_f32 v[138:139], v[18:19], v[18:19], v[138:139]
	v_pk_fma_f32 v[140:141], v[20:21], v[20:21], v[140:141]
	v_cvt_pk_bf16_f32 v22, v22, v23
	v_cvt_pk_bf16_f32 v23, v24, v25
	v_cvt_pk_bf16_f32 v24, v18, v19
	v_cvt_pk_bf16_f32 v25, v20, v21
	global_store_dwordx4 v253, v[22:25], s[28:29] offset:256
	v_pk_add_f32 v[138:139], v[138:139], v[140:141]
	s_nop 0
	v_add_f32_e32 v124, v138, v139
	v_add_u32_e32 v253, 0x58000, v243
	s_waitcnt vmcnt(1)
; DI u32x2 pk4(f32x4 v) { u32x2 r; r.x = cvt_pk(v[0], v[1]); r.y = cvt_pk(v[2], v[3]); return r; }
; DI void gemm_phase(LAS unsigned char* lds, const GemmDesc& d, float* __restrict__ X) {
;     ...
;         for (int m = 0; m < 4; ++m) {
;           const int row = pm * 256 + 128 * ai + 16 * m + rb; float ss = 0.f;
; #pragma unroll
;           for (int bj = 0; bj < 2; ++bj) {
;             const size_t o = (size_t)row * DM + pn * 256 + 128 * bj + cb;
;             const u32x4 xw = *(const u32x4*)(d.O0 + o); u32x4 ow;
; #pragma unroll
;             for (int n = 0; n < 2; ++n) {
;               const unsigned w0 = n ? xw.z : xw.x, w1 = n ? xw.w : xw.y;
;               f32x4 xo; xo[0] = __uint_as_float(w0 << 16); xo[1] = __uint_as_float(w0 & 0xffff0000u); xo[2] = __uint_as_float(w1 << 16); xo[3] = __uint_as_float(w1 & 0xffff0000u);
;               const f32x4 xn = xo + acc[ai][bj][m][n] * alpha;
;               ss += (xn[0] * xn[0] + xn[1] * xn[1]) + (xn[2] * xn[2] + xn[3] * xn[3]);
;               const u32x2 pw = pk4(xn); if (n) { ow.z = pw.x; ow.w = pw.y; } else { ow.x = pw.x; ow.y = pw.y; }
;             }
;             *(u32x4*)(d.O0 + o) = ow;
;           }
;           ss += __shfl_xor(ss, 16); ss += __shfl_xor(ss, 32);
;           if (fq == 0) red[wc * 256 + 128 * ai + 16 * m + rb] = ss;
	v_lshlrev_b32_e32 v130, 16, v170
	v_and_b32_e32 v131, 0xffff0000, v170
	v_lshlrev_b32_e32 v132, 16, v171
	v_and_b32_e32 v133, 0xffff0000, v171
	v_lshlrev_b32_e32 v134, 16, v172
	v_and_b32_e32 v135, 0xffff0000, v172
	v_lshlrev_b32_e32 v136, 16, v173
	v_and_b32_e32 v137, 0xffff0000, v173
	v_pk_fma_f32 v[14:15], s[60:61], v[14:15], v[130:131]
	v_pk_fma_f32 v[16:17], s[66:67], v[16:17], v[132:133]
	v_pk_fma_f32 v[10:11], s[60:61], v[10:11], v[134:135]
	v_pk_fma_f32 v[12:13], s[66:67], v[12:13], v[136:137]
	v_pk_mul_f32 v[138:139], v[14:15], v[14:15]
	v_pk_mul_f32 v[140:141], v[16:17], v[16:17]
	v_pk_fma_f32 v[138:139], v[10:11], v[10:11], v[138:139]
	v_pk_fma_f32 v[140:141], v[12:13], v[12:13], v[140:141]
	v_cvt_pk_bf16_f32 v14, v14, v15
	v_cvt_pk_bf16_f32 v15, v16, v17
	v_cvt_pk_bf16_f32 v16, v10, v11
	v_cvt_pk_bf16_f32 v17, v12, v13
	global_store_dwordx4 v253, v[14:17], s[28:29]
	s_waitcnt vmcnt(0)
	v_lshlrev_b32_e32 v130, 16, v184
	v_and_b32_e32 v131, 0xffff0000, v184
	v_lshlrev_b32_e32 v132, 16, v185
	v_and_b32_e32 v133, 0xffff0000, v185
	v_lshlrev_b32_e32 v134, 16, v186
	v_and_b32_e32 v135, 0xffff0000, v186
	v_lshlrev_b32_e32 v136, 16, v187
	v_and_b32_e32 v137, 0xffff0000, v187
	v_pk_fma_f32 v[6:7], s[60:61], v[6:7], v[130:131]
	v_pk_fma_f32 v[8:9], s[66:67], v[8:9], v[132:133]
	v_pk_fma_f32 v[2:3], s[60:61], v[2:3], v[134:135]
	v_pk_fma_f32 v[4:5], s[66:67], v[4:5], v[136:137]
	v_pk_fma_f32 v[138:139], v[6:7], v[6:7], v[138:139]
	v_pk_fma_f32 v[140:141], v[8:9], v[8:9], v[140:141]
	v_pk_fma_f32 v[138:139], v[2:3], v[2:3], v[138:139]
	v_pk_fma_f32 v[140:141], v[4:5], v[4:5], v[140:141]
	v_cvt_pk_bf16_f32 v6, v6, v7
	v_cvt_pk_bf16_f32 v7, v8, v9
	v_cvt_pk_bf16_f32 v8, v2, v3
	v_cvt_pk_bf16_f32 v9, v4, v5
	global_store_dwordx4 v253, v[6:9], s[28:29] offset:256
	v_pk_add_f32 v[138:139], v[138:139], v[140:141]
	s_nop 0
	v_add_f32_e32 v125, v138, v139
	v_mov_b32_e32 v130, v114
	v_mov_b32_e32 v131, v115
	v_mov_b32_e32 v132, v116
	v_mov_b32_e32 v133, v117
	v_mov_b32_e32 v134, v122
	v_mov_b32_e32 v135, v123
	v_mov_b32_e32 v136, v124
	v_mov_b32_e32 v137, v125
	s_nop 1
	v_permlane16_swap_b32 v114, v130
	v_permlane16_swap_b32 v115, v131
	v_permlane16_swap_b32 v116, v132
	v_permlane16_swap_b32 v117, v133
	v_permlane16_swap_b32 v122, v134
	v_permlane16_swap_b32 v123, v135
	v_permlane16_swap_b32 v124, v136
	v_permlane16_swap_b32 v125, v137
	s_nop 1
	v_add_f32_e32 v114, v114, v130
	v_add_f32_e32 v115, v115, v131
	v_add_f32_e32 v116, v116, v132
	v_add_f32_e32 v117, v117, v133
	v_add_f32_e32 v122, v122, v134
	v_add_f32_e32 v123, v123, v135
	v_add_f32_e32 v124, v124, v136
	v_add_f32_e32 v125, v125, v137
	v_mov_b32_e32 v130, v114
	v_mov_b32_e32 v131, v115
	v_mov_b32_e32 v132, v116
	v_mov_b32_e32 v133, v117
	v_mov_b32_e32 v134, v122
	v_mov_b32_e32 v135, v123
	v_mov_b32_e32 v136, v124
	v_mov_b32_e32 v137, v125
	s_nop 1
	v_permlane32_swap_b32 v114, v130
	v_permlane32_swap_b32 v115, v131
	v_permlane32_swap_b32 v116, v132
	v_permlane32_swap_b32 v117, v133
	v_permlane32_swap_b32 v122, v134
	v_permlane32_swap_b32 v123, v135
	v_permlane32_swap_b32 v124, v136
	v_permlane32_swap_b32 v125, v137
	s_nop 1
	v_add_f32_e32 v114, v114, v130
	v_add_f32_e32 v115, v115, v131
	v_add_f32_e32 v116, v116, v132
	v_add_f32_e32 v117, v117, v133
	v_add_f32_e32 v122, v122, v134
	v_add_f32_e32 v123, v123, v135
	v_add_f32_e32 v124, v124, v136
	v_add_f32_e32 v125, v125, v137
	s_and_saveexec_b64 s[44:45], vcc
	ds_write_b32 v0, v114
	ds_write_b32 v0, v115 offset:64
	ds_write_b32 v0, v116 offset:128
	ds_write_b32 v0, v117 offset:192
	ds_write_b32 v0, v122 offset:512
	ds_write_b32 v0, v123 offset:576
	ds_write_b32 v0, v124 offset:640
	ds_write_b32 v0, v125 offset:704
